# attention loops: rescale-path v_pk_mul_f32 (broadcast form) split into scalar v_mul_f32 pairs
# baseline (speedup 1.0000x reference)
; DI float fexp2(float x) { return __builtin_amdgcn_exp2f(x); }
; DI float max3f(float a, float b, float c) { float r; asm("v_max3_f32 %0, %1, %2, %3" : "=v"(r) : "v"(a), "v"(b), "v"(c)); return r; }
; DI float max2f(float a, float b) { float r; asm("v_max_f32_e32 %0, %1, %2" : "=v"(r) : "v"(a), "v"(b)); return r; }
;     ...
;             float mxa = max3f(s0[0], s1[0], s0[1]), mxb = max3f(s1[1], s0[2], s1[2]);
; #pragma unroll
;             for (int i = 3; i < 15; i += 2) { mxa = max3f(mxa, s0[i], s1[i]); mxb = max3f(mxb, s0[i + 1], s1[i + 1]); }
;             float mx = max3f(mxa, mxb, max2f(s0[15], s1[15]));
;             mx = max2f(mx, __shfl_xor(mx, 32));
;             if (__builtin_amdgcn_ballot_w64(mx - m > 8.0f) != 0ull) {
;                 const float mn = fmaxf(m, mx), mu_ = (mn == -INFINITY) ? 0.f : mn;
;                 const float alpha = fexp2(m - mu_); m = mn; l *= alpha;
; #pragma unroll
;                 for (int i = 0; i < 16; ++i) { o0[i] *= alpha; o1[i] *= alpha; }
;             }
.LBB0_135:
	v_max3_f32 v128, v66, v82, v67
	v_max3_f32 v129, v83, v68, v84
	v_max_f32_e32 v146, v81, v97
	s_mov_b32 s8, 0x41000000
	v_max3_f32 v128, v128, v69, v85
	v_max3_f32 v129, v129, v70, v86
	s_nop 0
	v_max3_f32 v128, v128, v71, v87
	v_max3_f32 v129, v129, v72, v88
	s_nop 0
	v_max3_f32 v128, v128, v73, v89
	v_max3_f32 v129, v129, v74, v90
	s_nop 0
	v_max3_f32 v128, v128, v75, v91
	v_max3_f32 v129, v129, v76, v92
	s_nop 0
	v_max3_f32 v128, v128, v77, v93
	v_max3_f32 v129, v129, v78, v94
	s_nop 0
	v_max3_f32 v128, v128, v79, v95
	v_max3_f32 v129, v129, v80, v96
	s_nop 0
	v_max3_f32 v128, v128, v129, v146
	v_mov_b32_e32 v129, v128
	s_nop 1
	v_permlane32_swap_b32_e32 v129, v128
	v_max_f32_e32 v128, v128, v129
	s_nop 0
	v_sub_f32_e32 v129, v128, v127
	v_cmp_lt_f32_e32 vcc, s8, v129
	s_cbranch_vccz .LBB0_137
	v_max_f32_e32 v128, v128, v128
	v_max_f32_e32 v129, v127, v127
	v_max_f32_e32 v129, v129, v128
	v_cmp_neq_f32_e32 vcc, s79, v129
	s_nop 1
	v_cndmask_b32_e32 v128, 0, v129, vcc
	v_sub_f32_e32 v127, v127, v128
	v_exp_f32_e32 v128, v127
	v_mov_b32_e32 v127, v129
	v_mul_f32_e32 v201, v201, v128
	v_mul_f32_e32 v48, v48, v128
	v_mul_f32_e32 v49, v49, v128
	v_mul_f32_e32 v46, v46, v128
	v_mul_f32_e32 v47, v47, v128
	v_mul_f32_e32 v44, v44, v128
	v_mul_f32_e32 v45, v45, v128
	v_mul_f32_e32 v42, v42, v128
	v_mul_f32_e32 v43, v43, v128
	v_mul_f32_e32 v40, v40, v128
	v_mul_f32_e32 v41, v41, v128
	v_mul_f32_e32 v38, v38, v128
	v_mul_f32_e32 v39, v39, v128
	v_mul_f32_e32 v36, v36, v128
	v_mul_f32_e32 v37, v37, v128
	v_mul_f32_e32 v34, v34, v128
	v_mul_f32_e32 v35, v35, v128
	v_mul_f32_e32 v64, v64, v128
	v_mul_f32_e32 v65, v65, v128
	v_mul_f32_e32 v62, v62, v128
	v_mul_f32_e32 v63, v63, v128
	v_mul_f32_e32 v60, v60, v128
	v_mul_f32_e32 v61, v61, v128
	v_mul_f32_e32 v58, v58, v128
	v_mul_f32_e32 v59, v59, v128
	v_mul_f32_e32 v56, v56, v128
	v_mul_f32_e32 v57, v57, v128
	v_mul_f32_e32 v54, v54, v128
	v_mul_f32_e32 v55, v55, v128
	v_mul_f32_e32 v52, v52, v128
	v_mul_f32_e32 v53, v53, v128
	v_mul_f32_e32 v50, v50, v128
	v_mul_f32_e32 v51, v51, v128

; DI float fexp2(float x) { return __builtin_amdgcn_exp2f(x); }
; DI float max3f(float a, float b, float c) { float r; asm("v_max3_f32 %0, %1, %2, %3" : "=v"(r) : "v"(a), "v"(b), "v"(c)); return r; }
; DI float max2f(float a, float b) { float r; asm("v_max_f32_e32 %0, %1, %2" : "=v"(r) : "v"(a), "v"(b)); return r; }
;     ...
;             float mxa = max3f(s0[0], s1[0], s0[1]), mxb = max3f(s1[1], s0[2], s1[2]);
; #pragma unroll
;             for (int i = 3; i < 15; i += 2) { mxa = max3f(mxa, s0[i], s1[i]); mxb = max3f(mxb, s0[i + 1], s1[i + 1]); }
;             float mx = max3f(mxa, mxb, max2f(s0[15], s1[15]));
;             mx = max2f(mx, __shfl_xor(mx, 32));
;             if (__builtin_amdgcn_ballot_w64(mx - m > 8.0f) != 0ull) {
;                 const float mn = fmaxf(m, mx), mu_ = (mn == -INFINITY) ? 0.f : mn;
;                 const float alpha = fexp2(m - mu_); m = mn; l *= alpha;
; #pragma unroll
;                 for (int i = 0; i < 16; ++i) { o0[i] *= alpha; o1[i] *= alpha; }
;             }
.LBB0_153:
	v_max3_f32 v202, v98, v114, v99
	v_max3_f32 v203, v115, v100, v116
	v_max_f32_e32 v204, v113, v129
	s_mov_b32 s0, 0x41000000
	v_max3_f32 v202, v202, v101, v117
	v_max3_f32 v203, v203, v102, v118
	s_nop 0
	v_max3_f32 v202, v202, v103, v119
	v_max3_f32 v203, v203, v104, v120
	s_nop 0
	v_max3_f32 v202, v202, v105, v121
	v_max3_f32 v203, v203, v106, v122
	s_nop 0
	v_max3_f32 v202, v202, v107, v123
	v_max3_f32 v203, v203, v108, v124
	s_nop 0
	v_max3_f32 v202, v202, v109, v125
	v_max3_f32 v203, v203, v110, v126
	s_nop 0
	v_max3_f32 v202, v202, v111, v127
	v_max3_f32 v203, v203, v112, v128
	s_nop 0
	v_max3_f32 v202, v202, v203, v204
	v_mov_b32_e32 v203, v202
	s_nop 1
	v_permlane32_swap_b32_e32 v203, v202
	v_max_f32_e32 v214, v202, v203
	s_nop 0
	v_sub_f32_e32 v202, v214, v213
	v_cmp_lt_f32_e32 vcc, s0, v202
	s_cbranch_vccz .LBB0_155
	v_max_f32_e32 v202, v214, v214
	v_max_f32_e32 v203, v213, v213
	v_max_f32_e32 v203, v203, v202
	v_cmp_neq_f32_e32 vcc, s79, v203
	s_nop 1
	v_cndmask_b32_e32 v202, 0, v203, vcc
	v_sub_f32_e32 v202, v213, v202
	v_exp_f32_e32 v202, v202
	v_mov_b32_e32 v213, v203
	v_mul_f32_e32 v211, v211, v202
	v_mul_f32_e32 v80, v80, v202
	v_mul_f32_e32 v81, v81, v202
	v_mul_f32_e32 v78, v78, v202
	v_mul_f32_e32 v79, v79, v202
	v_mul_f32_e32 v76, v76, v202
	v_mul_f32_e32 v77, v77, v202
	v_mul_f32_e32 v74, v74, v202
	v_mul_f32_e32 v75, v75, v202
	v_mul_f32_e32 v72, v72, v202
	v_mul_f32_e32 v73, v73, v202
	v_mul_f32_e32 v70, v70, v202
	v_mul_f32_e32 v71, v71, v202
	v_mul_f32_e32 v68, v68, v202
	v_mul_f32_e32 v69, v69, v202
	v_mul_f32_e32 v66, v66, v202
	v_mul_f32_e32 v67, v67, v202
	v_mul_f32_e32 v96, v96, v202
	v_mul_f32_e32 v97, v97, v202
	v_mul_f32_e32 v94, v94, v202
	v_mul_f32_e32 v95, v95, v202
	v_mul_f32_e32 v92, v92, v202
	v_mul_f32_e32 v93, v93, v202
	v_mul_f32_e32 v90, v90, v202
	v_mul_f32_e32 v91, v91, v202
	v_mul_f32_e32 v88, v88, v202
	v_mul_f32_e32 v89, v89, v202
	v_mul_f32_e32 v86, v86, v202
	v_mul_f32_e32 v87, v87, v202
	v_mul_f32_e32 v84, v84, v202
	v_mul_f32_e32 v85, v85, v202
	v_mul_f32_e32 v82, v82, v202
	v_mul_f32_e32 v83, v83, v202

; DI void phase_att1(const Ctx& C, const KA& a) {
;     ...
;             l += __shfl_xor(l, 32); const float sc = g_slc / l;
; #pragma unroll
;             for (int i = 0; i < 16; ++i) { r0[i] += sc * o0[i]; r1[i] += sc * o1[i]; }
;         }
;         {
;             f32x16 o0, o1; zero16(o0); zero16(o1); float m = -INFINITY, l = 0.f;
;             const int wlo = tg > 8 ? tg - 8 : 0;
;             attn_tiles_lds<64, true, false>(o0, o1, m, l, qf, (const char*)(z + (size_t)(b * SEQ) * LD1 + Z1_KW + g * 64), (size_t)LD1 * 2, (const char*)(vt + 2 * VTS + (size_t)bg * 64 * SEQ), (size_t)SEQ * 2,
;                                             wlo, tg, t, 8 * tt, 8 * tt + 7, 512, t5 + head * TABW, 0u, wlo, tg, C.lds, 73728, C.tid, n, h);
;             l += __shfl_xor(l, 32); const float sc = g_win / l;
; #pragma unroll
;             for (int i = 0; i < 16; ++i) { r0[i] += sc * o0[i]; r1[i] += sc * o1[i]; }
;         }
;         { int tok2 = b * SEQ + t; asm volatile("" : "+v"(tok2));
;           store_o64(mixed + (size_t)tok2 * DM + 512 + head * 64, r0, r1, 1.0f, h); }
.LBB0_160:
	v_add_f32_e32 v0, v201, v208
	v_div_scale_f32 v98, s[8:9], v0, v0, v200
	v_rcp_f32_e32 v99, v98
	v_div_scale_f32 v100, vcc, v200, v0, v200
	v_fma_f32 v101, -v98, v99, 1.0
	v_fmac_f32_e32 v99, v101, v99
	v_mul_f32_e32 v101, v100, v99
	v_fma_f32 v102, -v98, v101, v100
	v_fmac_f32_e32 v101, v102, v99
	v_fma_f32 v98, -v98, v101, v100
	v_div_fmas_f32 v98, v98, v99, v101
	v_div_fixup_f32 v98, v98, v0, v200
	v_mul_f32_e32 v36, v36, v98
	v_mul_f32_e32 v37, v37, v98
	ds_bpermute_b32 v0, v167, v211
	v_pk_fma_f32 v[4:5], v[180:181], v[4:5], v[36:37] op_sel_hi:[0,1,1]
	v_pk_mul_f32 v[36:37], v[52:53], v[98:99] op_sel_hi:[1,0]
	v_readlane_b32 s0, v254, 13
	v_pk_fma_f32 v[20:21], v[180:181], v[20:21], v[36:37] op_sel_hi:[0,1,1]
	v_pk_mul_f32 v[36:37], v[38:39], v[98:99] op_sel_hi:[1,0]
	s_waitcnt lgkmcnt(0)
	v_add_f32_e32 v0, v211, v0
	v_pk_fma_f32 v[6:7], v[180:181], v[6:7], v[36:37] op_sel_hi:[0,1,1]
	v_pk_mul_f32 v[36:37], v[54:55], v[98:99] op_sel_hi:[1,0]
	v_readlane_b32 s1, v254, 14
	v_pk_fma_f32 v[22:23], v[180:181], v[22:23], v[36:37] op_sel_hi:[0,1,1]
	v_pk_mul_f32 v[36:37], v[40:41], v[98:99] op_sel_hi:[1,0]
	v_pk_mul_f32 v[2:3], v[180:181], v[2:3] op_sel_hi:[0,1]
	v_pk_fma_f32 v[8:9], v[180:181], v[8:9], v[36:37] op_sel_hi:[0,1,1]
	v_pk_mul_f32 v[36:37], v[56:57], v[98:99] op_sel_hi:[1,0]
	v_pk_fma_f32 v[2:3], v[34:35], v[98:99], v[2:3] op_sel_hi:[1,0,1]
	v_pk_fma_f32 v[24:25], v[180:181], v[24:25], v[36:37] op_sel_hi:[0,1,1]
	v_pk_mul_f32 v[36:37], v[42:43], v[98:99] op_sel_hi:[1,0]
	s_movk_i32 s58, 0x2000
	v_pk_fma_f32 v[10:11], v[180:181], v[10:11], v[36:37] op_sel_hi:[0,1,1]
	v_pk_mul_f32 v[36:37], v[58:59], v[98:99] op_sel_hi:[1,0]
	s_nop 0
	v_pk_fma_f32 v[26:27], v[180:181], v[26:27], v[36:37] op_sel_hi:[0,1,1]
	v_pk_mul_f32 v[36:37], v[44:45], v[98:99] op_sel_hi:[1,0]
	s_nop 0
	v_pk_fma_f32 v[12:13], v[180:181], v[12:13], v[36:37] op_sel_hi:[0,1,1]
	v_pk_mul_f32 v[36:37], v[60:61], v[98:99] op_sel_hi:[1,0]
	s_nop 0
	v_pk_fma_f32 v[28:29], v[180:181], v[28:29], v[36:37] op_sel_hi:[0,1,1]
	v_add_f32_e32 v36, 1.0, v179
	v_rcp_f32_e32 v38, v36
	v_pk_mul_f32 v[36:37], v[46:47], v[98:99] op_sel_hi:[1,0]
	v_ashrrev_i32_e32 v179, 31, v178
	v_pk_fma_f32 v[14:15], v[180:181], v[14:15], v[36:37] op_sel_hi:[0,1,1]
	v_div_scale_f32 v39, s[8:9], v0, v0, v38
	v_rcp_f32_e32 v40, v39
	v_pk_mul_f32 v[36:37], v[62:63], v[98:99] op_sel_hi:[1,0]
	s_nop 0
	v_pk_fma_f32 v[30:31], v[180:181], v[30:31], v[36:37] op_sel_hi:[0,1,1]
	v_fma_f32 v36, -v39, v40, 1.0
	v_fmac_f32_e32 v40, v36, v40
	v_div_scale_f32 v36, vcc, v38, v0, v38
	v_mul_f32_e32 v37, v36, v40
	v_fma_f32 v41, -v39, v37, v36
	v_fmac_f32_e32 v37, v41, v40
	v_fma_f32 v36, -v39, v37, v36
	v_div_fmas_f32 v36, v36, v40, v37
	v_div_fixup_f32 v36, v36, v0, v38
	v_pk_mul_f32 v[38:39], v[48:49], v[98:99] op_sel_hi:[1,0]
	v_lshlrev_b32_e32 v0, 1, v199
	v_pk_fma_f32 v[16:17], v[180:181], v[16:17], v[38:39] op_sel_hi:[0,1,1]
	v_pk_mul_f32 v[38:39], v[64:65], v[98:99] op_sel_hi:[1,0]
	v_pk_fma_f32 v[4:5], v[68:69], v[36:37], v[4:5] op_sel_hi:[1,0,1]
	v_pk_fma_f32 v[32:33], v[180:181], v[32:33], v[38:39] op_sel_hi:[0,1,1]
	v_lshlrev_b64 v[38:39], 11, v[178:179]
	v_lshl_add_u64 v[38:39], s[0:1], 0, v[38:39]
	v_lshl_add_u64 v[38:39], v[38:39], 0, v[0:1]
	v_lshlrev_b32_e32 v0, 1, v176
	v_pk_fma_f32 v[2:3], v[66:67], v[36:37], v[2:3] op_sel_hi:[1,0,1]
	v_lshl_add_u64 v[38:39], v[38:39], 0, v[0:1]
	v_cvt_pk_bf16_f32 v2, v2, v3
	v_cvt_pk_bf16_f32 v3, v4, v5
	global_store_dwordx2 v[38:39], v[2:3], off offset:1024
	v_pk_mul_f32 v[2:3], v[180:181], v[18:19] op_sel_hi:[0,1]
	v_pk_fma_f32 v[2:3], v[50:51], v[98:99], v[2:3] op_sel_hi:[1,0,1]
	v_pk_fma_f32 v[20:21], v[84:85], v[36:37], v[20:21] op_sel_hi:[1,0,1]
	v_pk_fma_f32 v[2:3], v[82:83], v[36:37], v[2:3] op_sel_hi:[1,0,1]
	v_pk_fma_f32 v[6:7], v[70:71], v[36:37], v[6:7] op_sel_hi:[1,0,1]
	v_pk_fma_f32 v[8:9], v[72:73], v[36:37], v[8:9] op_sel_hi:[1,0,1]
	v_cvt_pk_bf16_f32 v2, v2, v3
	v_cvt_pk_bf16_f32 v3, v20, v21
	v_pk_fma_f32 v[22:23], v[86:87], v[36:37], v[22:23] op_sel_hi:[1,0,1]
	v_pk_fma_f32 v[24:25], v[88:89], v[36:37], v[24:25] op_sel_hi:[1,0,1]
	global_store_dwordx2 v[38:39], v[2:3], off offset:1088
	v_cvt_pk_bf16_f32 v2, v6, v7
	v_cvt_pk_bf16_f32 v3, v8, v9
	v_pk_fma_f32 v[10:11], v[74:75], v[36:37], v[10:11] op_sel_hi:[1,0,1]
	v_pk_fma_f32 v[12:13], v[76:77], v[36:37], v[12:13] op_sel_hi:[1,0,1]
	global_store_dwordx2 v[38:39], v[2:3], off offset:1040
	v_cvt_pk_bf16_f32 v2, v22, v23
	v_cvt_pk_bf16_f32 v3, v24, v25
	v_pk_fma_f32 v[26:27], v[90:91], v[36:37], v[26:27] op_sel_hi:[1,0,1]
	v_pk_fma_f32 v[28:29], v[92:93], v[36:37], v[28:29] op_sel_hi:[1,0,1]
	global_store_dwordx2 v[38:39], v[2:3], off offset:1104
	v_cvt_pk_bf16_f32 v2, v10, v11
	v_cvt_pk_bf16_f32 v3, v12, v13
	v_pk_fma_f32 v[14:15], v[78:79], v[36:37], v[14:15] op_sel_hi:[1,0,1]
	v_pk_fma_f32 v[16:17], v[80:81], v[36:37], v[16:17] op_sel_hi:[1,0,1]
	global_store_dwordx2 v[38:39], v[2:3], off offset:1056
	v_cvt_pk_bf16_f32 v2, v26, v27
	v_cvt_pk_bf16_f32 v3, v28, v29
	v_pk_fma_f32 v[30:31], v[94:95], v[36:37], v[30:31] op_sel_hi:[1,0,1]
	v_pk_fma_f32 v[32:33], v[96:97], v[36:37], v[32:33] op_sel_hi:[1,0,1]
	global_store_dwordx2 v[38:39], v[2:3], off offset:1120
	v_cvt_pk_bf16_f32 v2, v14, v15
	v_cvt_pk_bf16_f32 v3, v16, v17
	global_store_dwordx2 v[38:39], v[2:3], off offset:1072
	v_cvt_pk_bf16_f32 v2, v30, v31
	v_cvt_pk_bf16_f32 v3, v32, v33
	global_store_dwordx2 v[38:39], v[2:3], off offset:1136
	s_mov_b32 s10, 0

; DI unsigned cvtpk(float lo, float hi) { f32x2_t v = {lo, hi}; bf16x2_t b = __builtin_convertvector(v, bf16x2_t); return __builtin_bit_cast(unsigned, b); }
; DI float fexp2(float x) { return __builtin_amdgcn_exp2f(x); }
; DI void store_o64(bf16_t* dst, const f32x16& o0, const f32x16& o1, float sc, int h) {
; #pragma unroll
;     for (int q = 0; q < 4; ++q) {
;         u32x2 w; w.x = cvtpk(o0[4 * q] * sc, o0[4 * q + 1] * sc); w.y = cvtpk(o0[4 * q + 2] * sc, o0[4 * q + 3] * sc);
;         *(u32x2*)(dst + 8 * q + 4 * h) = w;
;         u32x2 w2; w2.x = cvtpk(o1[4 * q] * sc, o1[4 * q + 1] * sc); w2.y = cvtpk(o1[4 * q + 2] * sc, o1[4 * q + 3] * sc);
;         *(u32x2*)(dst + 32 + 8 * q + 4 * h) = w2;
;     }
; DI void phase_att1(const Ctx& C, const KA& a) {
;     ...
;             l += __shfl_xor(l, 32);
;             const float sk = sinks[head] * LOG2E; const float mf = fmaxf(m, sk);
;             const float den = l * fexp2(m - mf) + fexp2(sk - mf);
;             store_o64(mixed + (size_t)tok * DM + head * 64, o0, o1, fexp2(m - mf) / den, h);
.LBB0_182:
	s_load_dwordx2 s[4:5], s[68:69], 0xc0
	v_lshlrev_b32_e32 v35, 2, v101
	v_max_f32_e32 v37, v115, v115
	ds_bpermute_b32 v34, v110, v113
	v_ashrrev_i32_e32 v103, 31, v102
	s_waitcnt lgkmcnt(0)
	global_load_dword v35, v35, s[4:5]
	s_mov_b32 s4, 0x3fb8aa3b
	v_readlane_b32 s0, v254, 13
	v_add_f32_e32 v34, v113, v34
	v_lshlrev_b32_e32 v0, 6, v101
	v_readlane_b32 s1, v254, 14
	v_lshlrev_b32_e32 v0, 1, v0
	v_mov_b32_e32 v101, v1
	s_add_i32 s11, s11, s39
	s_cmpk_lt_i32 s11, 0x400
	s_waitcnt vmcnt(0)
	v_mul_f32_e32 v36, 0x3fb8aa3b, v35
	v_max_f32_e32 v36, v37, v36
	v_sub_f32_e32 v37, v115, v36
	v_fma_f32 v35, v35, s4, -v36
	v_exp_f32_e32 v37, v37
	v_exp_f32_e32 v36, v35
	s_nop 0
	v_fmac_f32_e32 v36, v34, v37
	v_lshlrev_b64 v[34:35], 11, v[102:103]
	v_lshl_add_u64 v[34:35], s[0:1], 0, v[34:35]
	v_lshl_add_u64 v[34:35], v[34:35], 0, v[0:1]
	v_div_scale_f32 v0, s[4:5], v36, v36, v37
	v_rcp_f32_e32 v38, v0
	v_lshl_add_u64 v[34:35], v[34:35], 0, v[100:101]
	v_fma_f32 v39, -v0, v38, 1.0
	v_fmac_f32_e32 v38, v39, v38
	v_div_scale_f32 v39, vcc, v37, v36, v37
	v_mul_f32_e32 v40, v39, v38
	v_fma_f32 v41, -v0, v40, v39
	v_fmac_f32_e32 v40, v41, v38
	v_fma_f32 v0, -v0, v40, v39
	v_div_fmas_f32 v0, v0, v38, v40
	v_div_fixup_f32 v0, v0, v36, v37
	v_mul_f32_e32 v2, v2, v0
	v_mul_f32_e32 v3, v3, v0
	v_mul_f32_e32 v4, v4, v0
	v_mul_f32_e32 v5, v5, v0
	v_cvt_pk_bf16_f32 v2, v2, v3
	v_cvt_pk_bf16_f32 v3, v4, v5
	global_store_dwordx2 v[34:35], v[2:3], off offset:64
	v_pk_mul_f32 v[2:3], v[22:23], v[0:1] op_sel_hi:[1,0]
	v_pk_mul_f32 v[4:5], v[24:25], v[0:1] op_sel_hi:[1,0]
	v_cvt_pk_bf16_f32 v2, v2, v3
	v_cvt_pk_bf16_f32 v3, v4, v5
	global_store_dwordx2 v[34:35], v[2:3], off offset:16
	v_pk_mul_f32 v[2:3], v[6:7], v[0:1] op_sel_hi:[1,0]
	v_pk_mul_f32 v[4:5], v[8:9], v[0:1] op_sel_hi:[1,0]
	v_cvt_pk_bf16_f32 v2, v2, v3
	v_cvt_pk_bf16_f32 v3, v4, v5
	global_store_dwordx2 v[34:35], v[2:3], off offset:80
	v_pk_mul_f32 v[2:3], v[26:27], v[0:1] op_sel_hi:[1,0]
	v_pk_mul_f32 v[4:5], v[28:29], v[0:1] op_sel_hi:[1,0]
	v_cvt_pk_bf16_f32 v2, v2, v3
	v_cvt_pk_bf16_f32 v3, v4, v5
	global_store_dwordx2 v[34:35], v[2:3], off offset:32
	v_pk_mul_f32 v[2:3], v[10:11], v[0:1] op_sel_hi:[1,0]
	v_pk_mul_f32 v[4:5], v[12:13], v[0:1] op_sel_hi:[1,0]
	v_cvt_pk_bf16_f32 v2, v2, v3
	v_cvt_pk_bf16_f32 v3, v4, v5
	global_store_dwordx2 v[34:35], v[2:3], off offset:96
	v_pk_mul_f32 v[2:3], v[30:31], v[0:1] op_sel_hi:[1,0]
	v_pk_mul_f32 v[4:5], v[32:33], v[0:1] op_sel_hi:[1,0]
	v_cvt_pk_bf16_f32 v2, v2, v3
	v_cvt_pk_bf16_f32 v3, v4, v5
	v_mul_f32_e32 v18, v18, v0
	v_mul_f32_e32 v19, v19, v0
	v_mul_f32_e32 v20, v20, v0
	v_mul_f32_e32 v21, v21, v0
	global_store_dwordx2 v[34:35], v[2:3], off offset:48
	v_pk_mul_f32 v[2:3], v[14:15], v[0:1] op_sel_hi:[1,0]
	v_pk_mul_f32 v[4:5], v[16:17], v[0:1] op_sel_hi:[1,0]
	v_cvt_pk_bf16_f32 v18, v18, v19
	v_cvt_pk_bf16_f32 v19, v20, v21
	v_cvt_pk_bf16_f32 v2, v2, v3
	v_cvt_pk_bf16_f32 v3, v4, v5
	global_store_dwordx2 v[34:35], v[18:19], off
	global_store_dwordx2 v[34:35], v[2:3], off offset:112
	s_cbranch_scc0 .LBB0_199

; DI float fexp2(float x) { return __builtin_amdgcn_exp2f(x); }
; DI float max3f(float a, float b, float c) { float r; asm("v_max3_f32 %0, %1, %2, %3" : "=v"(r) : "v"(a), "v"(b), "v"(c)); return r; }
; DI float max2f(float a, float b) { float r; asm("v_max_f32_e32 %0, %1, %2" : "=v"(r) : "v"(a), "v"(b)); return r; }
;     ...
;             float mxa = max3f(s0[0], s1[0], s0[1]), mxb = max3f(s1[1], s0[2], s1[2]);
; #pragma unroll
;             for (int i = 3; i < 15; i += 2) { mxa = max3f(mxa, s0[i], s1[i]); mxb = max3f(mxb, s0[i + 1], s1[i + 1]); }
;             float mx = max3f(mxa, mxb, max2f(s0[15], s1[15]));
;             mx = max2f(mx, __shfl_xor(mx, 32));
;             if (__builtin_amdgcn_ballot_w64(mx - m > 8.0f) != 0ull) {
;                 const float mn = fmaxf(m, mx), mu_ = (mn == -INFINITY) ? 0.f : mn;
;                 const float alpha = fexp2(m - mu_); m = mn; l *= alpha;
; #pragma unroll
;                 for (int i = 0; i < 16; ++i) { o0[i] *= alpha; o1[i] *= alpha; }
;             }
.LBB0_194:
	v_max3_f32 v116, v34, v50, v35
	v_max3_f32 v117, v51, v36, v52
	v_max_f32_e32 v118, v49, v65
	s_mov_b32 s0, 0x41000000
	v_max3_f32 v116, v116, v37, v53
	v_max3_f32 v117, v117, v38, v54
	s_nop 0
	v_max3_f32 v116, v116, v39, v55
	v_max3_f32 v117, v117, v40, v56
	s_nop 0
	v_max3_f32 v116, v116, v41, v57
	v_max3_f32 v117, v117, v42, v58
	s_nop 0
	v_max3_f32 v116, v116, v43, v59
	v_max3_f32 v117, v117, v44, v60
	s_nop 0
	v_max3_f32 v116, v116, v45, v61
	v_max3_f32 v117, v117, v46, v62
	s_nop 0
	v_max3_f32 v116, v116, v47, v63
	v_max3_f32 v117, v117, v48, v64
	s_nop 0
	v_max3_f32 v116, v116, v117, v118
	v_mov_b32_e32 v117, v116
	s_nop 1
	v_permlane32_swap_b32_e32 v117, v116
	v_max_f32_e32 v116, v116, v117
	s_nop 0
	v_sub_f32_e32 v117, v116, v115
	v_cmp_lt_f32_e32 vcc, s0, v117
	s_cbranch_vccz .LBB0_196
	v_max_f32_e32 v116, v116, v116
	v_max_f32_e32 v117, v115, v115
	v_max_f32_e32 v117, v117, v116
	v_cmp_neq_f32_e32 vcc, s79, v117
	s_nop 1
	v_cndmask_b32_e32 v116, 0, v117, vcc
	v_sub_f32_e32 v115, v115, v116
	v_exp_f32_e32 v116, v115
	v_mov_b32_e32 v115, v117
	v_mul_f32_e32 v113, v113, v116
	v_mul_f32_e32 v32, v32, v116
	v_mul_f32_e32 v33, v33, v116
	v_mul_f32_e32 v30, v30, v116
	v_mul_f32_e32 v31, v31, v116
	v_mul_f32_e32 v28, v28, v116
	v_mul_f32_e32 v29, v29, v116
	v_mul_f32_e32 v26, v26, v116
	v_mul_f32_e32 v27, v27, v116
	v_mul_f32_e32 v24, v24, v116
	v_mul_f32_e32 v25, v25, v116
	v_mul_f32_e32 v22, v22, v116
	v_mul_f32_e32 v23, v23, v116
	v_mul_f32_e32 v20, v20, v116
	v_mul_f32_e32 v21, v21, v116
	v_mul_f32_e32 v18, v18, v116
	v_mul_f32_e32 v19, v19, v116
	v_mul_f32_e32 v16, v16, v116
	v_mul_f32_e32 v17, v17, v116
	v_mul_f32_e32 v14, v14, v116
	v_mul_f32_e32 v15, v15, v116
	v_mul_f32_e32 v12, v12, v116
	v_mul_f32_e32 v13, v13, v116
	v_mul_f32_e32 v10, v10, v116
	v_mul_f32_e32 v11, v11, v116
	v_mul_f32_e32 v8, v8, v116
	v_mul_f32_e32 v9, v9, v116
	v_mul_f32_e32 v6, v6, v116
	v_mul_f32_e32 v7, v7, v116
	v_mul_f32_e32 v4, v4, v116
	v_mul_f32_e32 v5, v5, v116
	v_mul_f32_e32 v2, v2, v116
	v_mul_f32_e32 v3, v3, v116

;     __device__ __forceinline__ const float* in(int i) const { return *(const float* const __attribute__((address_space(4)))*)(k + 8 * i); }
; DI unsigned cvtpk(float lo, float hi) { f32x2_t v = {lo, hi}; bf16x2_t b = __builtin_convertvector(v, bf16x2_t); return __builtin_bit_cast(unsigned, b); }
; DI void cmp_item(const Ctx& C, const KA& a, int item) {
;     ...
;     if (which == 0) {
;         float ss = 0.f;
; #pragma unroll
;         for (int i = 0; i < 16; ++i) ss += o0[i] * o0[i] + o1[i] * o1[i];
;         ss += __shfl_xor(ss, 32);
;         const float r = 1.0f / sqrtf(ss * (1.0f / 64.0f) + EPS);
;         const float* kg = a.in(26);
;         bf16_t* dst = (bf16_t*)(ws + WS_KC) + ((size_t)(b * 2 + g) * 128 + c) * 64;
; #pragma unroll
;         for (int q = 0; q < 4; ++q) { const int f = 8 * q + 4 * h; const f32x4 g0 = *(const f32x4*)(kg + f), g1 = *(const f32x4*)(kg + 32 + f);
;             u32x2 w; w.x = cvtpk(o0[4 * q] * r * g0.x, o0[4 * q + 1] * r * g0.y); w.y = cvtpk(o0[4 * q + 2] * r * g0.z, o0[4 * q + 3] * r * g0.w); *(u32x2*)(dst + f) = w;
;             u32x2 w2; w2.x = cvtpk(o1[4 * q] * r * g1.x, o1[4 * q + 1] * r * g1.y); w2.y = cvtpk(o1[4 * q + 2] * r * g1.z, o1[4 * q + 3] * r * g1.w); *(u32x2*)(dst + 32 + f) = w2; }
.LBB0_209:
	s_andn2_b64 vcc, exec, s[4:5]
	s_cbranch_vccnz .LBB0_203
	s_nop 7
	v_mul_f32_e32 v0, v18, v18
	v_mul_f32_e32 v35, v19, v19
	v_fmac_f32_e32 v0, v2, v2
	v_fmac_f32_e32 v35, v3, v3
	v_add_f32_e32 v0, v0, v35
	v_mul_f32_e32 v35, v20, v20
	v_fmac_f32_e32 v35, v4, v4
	v_add_f32_e32 v0, v35, v0
	v_mul_f32_e32 v35, v21, v21
	v_fmac_f32_e32 v35, v5, v5
	v_add_f32_e32 v0, v35, v0
	v_mul_f32_e32 v35, v22, v22
	v_fmac_f32_e32 v35, v6, v6
	v_add_f32_e32 v0, v35, v0
	v_mul_f32_e32 v35, v23, v23
	v_fmac_f32_e32 v35, v7, v7
	v_add_f32_e32 v0, v35, v0
	v_mul_f32_e32 v35, v24, v24
	v_fmac_f32_e32 v35, v8, v8
	v_add_f32_e32 v0, v35, v0
	v_mul_f32_e32 v35, v25, v25
	v_fmac_f32_e32 v35, v9, v9
	v_add_f32_e32 v0, v35, v0
	v_mul_f32_e32 v35, v26, v26
	v_fmac_f32_e32 v35, v10, v10
	v_add_f32_e32 v0, v35, v0
	v_mul_f32_e32 v35, v27, v27
	v_fmac_f32_e32 v35, v11, v11
	v_pk_mul_f32 v[36:37], v[28:29], v[28:29]
	v_add_f32_e32 v0, v35, v0
	v_pk_fma_f32 v[36:37], v[12:13], v[12:13], v[36:37]
	v_pk_mul_f32 v[38:39], v[30:31], v[30:31]
	v_add_f32_e32 v0, v36, v0
	v_pk_fma_f32 v[38:39], v[14:15], v[14:15], v[38:39]
	v_add_f32_e32 v0, v37, v0
	v_and_b32_e32 v36, 64, v245
	v_pk_mul_f32 v[40:41], v[32:33], v[32:33]
	v_add_f32_e32 v0, v38, v0
	v_xor_b32_e32 v35, 32, v245
	v_add_u32_e32 v36, 64, v36
	v_pk_fma_f32 v[40:41], v[16:17], v[16:17], v[40:41]
	v_add_f32_e32 v0, v39, v0
	v_cmp_lt_i32_e32 vcc, v35, v36
	v_add_f32_e32 v0, v40, v0
	v_add_f32_e32 v0, v41, v0
	v_cndmask_b32_e32 v35, v245, v35, vcc
	v_lshlrev_b32_e32 v35, 2, v35
	ds_bpermute_b32 v35, v35, v0
	v_lshlrev_b32_e32 v43, 2, v66
	s_lshl_b32 s8, s52, 1
	s_or_b32 s8, s8, s14
	s_ashr_i32 s9, s8, 31
	s_waitcnt lgkmcnt(0)
	v_add_f32_e32 v0, v0, v35
	v_fmamk_f32 v0, v0, 0x3c800000, v241
	v_cmp_gt_f32_e32 vcc, s3, v0
	v_mul_f32_e32 v35, 0x4f800000, v0
	s_lshl_b64 s[8:9], s[8:9], 14
	v_cndmask_b32_e32 v0, v0, v35, vcc
	v_sqrt_f32_e32 v35, v0
	v_readlane_b32 s0, v254, 15
	s_add_u32 s8, s0, s8
	v_readlane_b32 s0, v254, 16
	v_add_u32_e32 v36, -1, v35
	v_fma_f32 v37, -v36, v35, v0
	v_cmp_ge_f32_e64 s[4:5], 0, v37
	v_add_u32_e32 v37, 1, v35
	s_addc_u32 s9, s0, s9
	v_cndmask_b32_e64 v36, v35, v36, s[4:5]
	v_fma_f32 v35, -v37, v35, v0
	v_cmp_lt_f32_e64 s[4:5], 0, v35
	s_nop 1
	v_cndmask_b32_e64 v35, v36, v37, s[4:5]
	v_mul_f32_e32 v36, 0x37800000, v35
	v_cndmask_b32_e32 v35, v35, v36, vcc
	v_cmp_class_f32_e32 vcc, v0, v242
	s_nop 1
	v_cndmask_b32_e32 v0, v35, v0, vcc
	v_div_scale_f32 v35, s[4:5], v0, v0, 1.0
	v_rcp_f32_e32 v36, v35
	s_load_dwordx2 s[4:5], s[68:69], 0xd0
	v_fma_f32 v37, -v35, v36, 1.0
	v_fmac_f32_e32 v36, v37, v36
	v_div_scale_f32 v37, vcc, 1.0, v0, 1.0
	v_mul_f32_e32 v38, v37, v36
	v_fma_f32 v39, -v35, v38, v37
	v_fmac_f32_e32 v38, v39, v36
	v_fma_f32 v35, -v35, v38, v37
	v_div_fmas_f32 v35, v35, v36, v38
	v_div_fixup_f32 v42, v35, v0, 1.0
	v_lshlrev_b32_e32 v0, 7, v34
	s_waitcnt lgkmcnt(0)
	global_load_dwordx4 v[34:37], v43, s[4:5]
	global_load_dwordx4 v[38:41], v43, s[4:5] offset:128
	v_mul_f32_e32 v2, v2, v42
	v_mul_f32_e32 v3, v3, v42
	v_lshl_add_u64 v[44:45], s[8:9], 0, v[0:1]
	v_lshlrev_b32_e32 v0, 1, v66
	s_waitcnt vmcnt(1)
	v_pk_mul_f32 v[2:3], v[34:35], v[2:3]
	s_nop 0
	v_cvt_pk_bf16_f32 v34, v2, v3
	v_pk_mul_f32 v[2:3], v[4:5], v[42:43] op_sel_hi:[1,0]
	v_pk_mul_f32 v[4:5], v[18:19], v[42:43] op_sel_hi:[1,0]
	v_pk_mul_f32 v[18:19], v[20:21], v[42:43] op_sel_hi:[1,0]
	v_pk_mul_f32 v[2:3], v[36:37], v[2:3]
	s_waitcnt vmcnt(0)
	v_pk_mul_f32 v[4:5], v[38:39], v[4:5]
	v_pk_mul_f32 v[18:19], v[40:41], v[18:19]
	v_cvt_pk_bf16_f32 v35, v2, v3
	v_lshl_add_u64 v[2:3], v[44:45], 0, v[0:1]
	v_cvt_pk_bf16_f32 v4, v4, v5
	v_cvt_pk_bf16_f32 v5, v18, v19
	global_store_dwordx2 v[2:3], v[34:35], off
	global_store_dwordx2 v[2:3], v[4:5], off offset:64
	global_load_dwordx4 v[18:21], v43, s[4:5] offset:32
	s_nop 0
	global_load_dwordx4 v[34:37], v43, s[4:5] offset:160
	v_pk_mul_f32 v[4:5], v[6:7], v[42:43] op_sel_hi:[1,0]
	v_pk_mul_f32 v[6:7], v[8:9], v[42:43] op_sel_hi:[1,0]
	v_pk_mul_f32 v[8:9], v[10:11], v[42:43] op_sel_hi:[1,0]
	s_waitcnt vmcnt(1)
	v_pk_mul_f32 v[4:5], v[4:5], v[18:19]
	v_pk_mul_f32 v[6:7], v[6:7], v[20:21]
	v_cvt_pk_bf16_f32 v4, v4, v5
	v_cvt_pk_bf16_f32 v5, v6, v7
	global_store_dwordx2 v[2:3], v[4:5], off offset:16
	v_pk_mul_f32 v[4:5], v[22:23], v[42:43] op_sel_hi:[1,0]
	v_pk_mul_f32 v[6:7], v[24:25], v[42:43] op_sel_hi:[1,0]
	s_waitcnt vmcnt(1)
	v_pk_mul_f32 v[4:5], v[4:5], v[34:35]
	v_pk_mul_f32 v[6:7], v[6:7], v[36:37]
	v_cvt_pk_bf16_f32 v4, v4, v5
	v_cvt_pk_bf16_f32 v5, v6, v7
	global_store_dwordx2 v[2:3], v[4:5], off offset:80
	global_load_dwordx4 v[4:7], v43, s[4:5] offset:64
	s_nop 0
	global_load_dwordx4 v[18:21], v43, s[4:5] offset:192
	s_waitcnt vmcnt(1)
	v_pk_mul_f32 v[4:5], v[8:9], v[4:5]
	v_pk_mul_f32 v[8:9], v[12:13], v[42:43] op_sel_hi:[1,0]
	v_cvt_pk_bf16_f32 v4, v4, v5
	v_pk_mul_f32 v[6:7], v[8:9], v[6:7]
	v_pk_mul_f32 v[12:13], v[14:15], v[42:43] op_sel_hi:[1,0]
	v_cvt_pk_bf16_f32 v5, v6, v7
	global_store_dwordx2 v[2:3], v[4:5], off offset:32
	v_pk_mul_f32 v[4:5], v[26:27], v[42:43] op_sel_hi:[1,0]
	v_pk_mul_f32 v[6:7], v[28:29], v[42:43] op_sel_hi:[1,0]
	s_waitcnt vmcnt(1)
	v_pk_mul_f32 v[4:5], v[4:5], v[18:19]
	v_pk_mul_f32 v[6:7], v[6:7], v[20:21]
	v_cvt_pk_bf16_f32 v4, v4, v5
	v_cvt_pk_bf16_f32 v5, v6, v7
	global_store_dwordx2 v[2:3], v[4:5], off offset:96
	global_load_dwordx4 v[4:7], v43, s[4:5] offset:96
	s_nop 0
	global_load_dwordx4 v[8:11], v43, s[4:5] offset:224
	s_waitcnt vmcnt(1)
	v_pk_mul_f32 v[4:5], v[12:13], v[4:5]
	v_pk_mul_f32 v[12:13], v[16:17], v[42:43] op_sel_hi:[1,0]
	v_cvt_pk_bf16_f32 v4, v4, v5
	v_pk_mul_f32 v[6:7], v[12:13], v[6:7]
	s_nop 0
	v_cvt_pk_bf16_f32 v5, v6, v7
	global_store_dwordx2 v[2:3], v[4:5], off offset:48
	v_pk_mul_f32 v[4:5], v[30:31], v[42:43] op_sel_hi:[1,0]
	v_pk_mul_f32 v[6:7], v[32:33], v[42:43] op_sel_hi:[1,0]
	s_waitcnt vmcnt(1)
	v_pk_mul_f32 v[4:5], v[4:5], v[8:9]
	v_pk_mul_f32 v[6:7], v[6:7], v[10:11]
	v_cvt_pk_bf16_f32 v4, v4, v5
	v_cvt_pk_bf16_f32 v5, v6, v7
	global_store_dwordx2 v[2:3], v[4:5], off offset:112
	s_branch .LBB0_203

; DI unsigned cvtpk(float lo, float hi) { f32x2_t v = {lo, hi}; bf16x2_t b = __builtin_convertvector(v, bf16x2_t); return __builtin_bit_cast(unsigned, b); }
; DI float bflo(unsigned u) { return __uint_as_float(u << 16); }
; DI float bfhi(unsigned u) { return __uint_as_float(u & 0xffff0000u); }
; DI float fexp2(float x) { return __builtin_amdgcn_exp2f(x); }
; DI void phase_comb0(const Ctx& C, const KA& a) {
;     ...
;         const int c8 = (int)(i & 7); const long th = i >> 3; const int hg = (int)(th & 3); const int tok = (int)(th >> 2);
;         const float l0 = lse[(size_t)tok * 4 + hg], l1 = lse[((size_t)TOK + tok) * 4 + hg], l2 = lse[((size_t)2 * TOK + tok) * 4 + hg];
;         const float mx = fmaxf(l0, fmaxf(l1, l2));
;         float w0 = fexp2(l0 - mx), w1 = fexp2(l1 - mx), w2 = fexp2(l2 - mx); const float inv = 1.0f / (w0 + w1 + w2); w0 *= inv; w1 *= inv; w2 *= inv;
;         const u32x4 a0 = *(const u32x4*)(og + ((size_t)tok * 4 + hg) * 64 + 8 * c8), a1 = *(const u32x4*)(og + (((size_t)TOK + tok) * 4 + hg) * 64 + 8 * c8), a2 = *(const u32x4*)(og + (((size_t)2 * TOK + tok) * 4 + hg) * 64 + 8 * c8);
;         u32x4 w;
; #pragma unroll
;         for (int j = 0; j < 4; ++j) w[j] = cvtpk(w0 * bflo(a0[j]) + w1 * bflo(a1[j]) + w2 * bflo(a2[j]), w0 * bfhi(a0[j]) + w1 * bfhi(a1[j]) + w2 * bfhi(a2[j]));
;         *(u32x4*)(z + (size_t)tok * LD0 + Z0_MIX + 512 + hg * 64 + 8 * c8) = w;
.LBB0_215:
	v_ashrrev_i32_e32 v3, 31, v11
	v_mov_b32_e32 v2, v11
	v_bfe_u32 v25, v6, 3, 2
	v_lshlrev_b64 v[2:3], 2, v[2:3]
	v_or_b32_e32 v2, v2, v25
	s_mov_b64 s[14:15], 0x20000
	v_lshl_add_u64 v[4:5], v[2:3], 2, s[0:1]
	v_lshl_add_u64 v[12:13], v[2:3], 0, s[14:15]
	global_load_dword v0, v[4:5], off
	v_lshl_add_u64 v[4:5], v[12:13], 2, s[0:1]
	s_waitcnt vmcnt(0)
	v_lshl_add_u64 v[16:17], v[2:3], 0, s[50:51]
	global_load_dword v14, v[4:5], off
	v_lshl_add_u64 v[4:5], v[16:17], 2, s[0:1]
	global_load_dword v4, v[4:5], off
	v_lshlrev_b64 v[2:3], 7, v[2:3]
	v_lshlrev_b64 v[12:13], 7, v[12:13]
	v_lshl_add_u64 v[2:3], s[20:21], 0, v[2:3]
	v_lshl_add_u64 v[12:13], s[20:21], 0, v[12:13]
	v_lshlrev_b64 v[16:17], 7, v[16:17]
	v_lshl_add_u64 v[16:17], s[20:21], 0, v[16:17]
	v_lshl_add_u64 v[6:7], v[6:7], 0, s[6:7]
	s_waitcnt vmcnt(0)
	v_max3_f32 v5, v0, v14, v4
	v_sub_f32_e32 v0, v0, v5
	v_exp_f32_e32 v21, v0
	v_sub_f32_e32 v0, v14, v5
	v_exp_f32_e32 v20, v0
	v_sub_f32_e32 v0, v4, v5
	v_exp_f32_e32 v0, v0
	v_add_f32_e32 v4, v21, v20
	v_add_f32_e32 v4, v0, v4
	v_div_scale_f32 v5, s[14:15], v4, v4, 1.0
	v_rcp_f32_e32 v14, v5
	s_nop 0
	v_fma_f32 v15, -v5, v14, 1.0
	v_fmac_f32_e32 v14, v15, v14
	v_div_scale_f32 v15, vcc, 1.0, v4, 1.0
	v_mul_f32_e32 v18, v15, v14
	s_waitcnt lgkmcnt(0)
	v_fma_f32 v19, -v5, v18, v15
	v_fmac_f32_e32 v18, v19, v14
	v_fma_f32 v5, -v5, v18, v15
	v_div_fmas_f32 v5, v5, v14, v18
	v_div_fixup_f32 v22, v5, v4, 1.0
	v_mul_f32_e32 v24, v0, v22
	v_lshlrev_b32_e32 v0, 1, v8
	v_and_b32_e32 v0, 0x70, v0
	v_lshl_add_u64 v[2:3], v[2:3], 0, v[0:1]
	v_lshl_add_u64 v[12:13], v[12:13], 0, v[0:1]
	global_load_dwordx4 v[2:5], v[2:3], off
	v_lshl_add_u64 v[16:17], v[16:17], 0, v[0:1]
	global_load_dwordx4 v[12:15], v[12:13], off
	v_mul_f32_e32 v20, v20, v22
	v_mul_f32_e32 v21, v21, v22
	global_load_dwordx4 v[16:19], v[16:17], off
	v_lshl_add_u64 v[8:9], v[8:9], 0, s[8:9]
	s_waitcnt vmcnt(2)
	v_lshlrev_b32_e32 v26, 16, v2
	v_and_b32_e32 v23, 0xffff0000, v2
	s_waitcnt vmcnt(1)
	v_and_b32_e32 v27, 0xffff0000, v12
	v_lshlrev_b32_e32 v22, 16, v12
	v_pk_mul_f32 v[26:27], v[20:21], v[26:27] op_sel:[1,0] op_sel_hi:[0,1]
	s_waitcnt vmcnt(0)
	v_lshlrev_b32_e32 v28, 16, v16
	v_and_b32_e32 v29, 0xffff0000, v16
	v_pk_fma_f32 v[22:23], v[20:21], v[22:23], v[26:27]
	v_lshlrev_b32_e32 v12, 16, v3
	v_pk_fma_f32 v[22:23], v[24:25], v[28:29], v[22:23] op_sel_hi:[0,1,1]
	v_cvt_pk_bf16_f32 v2, v22, v23
	v_lshlrev_b32_e32 v22, 16, v13
	v_and_b32_e32 v13, 0xffff0000, v13
	v_and_b32_e32 v23, 0xffff0000, v3
	v_pk_mul_f32 v[12:13], v[20:21], v[12:13] op_sel:[1,0] op_sel_hi:[0,1]
	v_lshlrev_b32_e32 v16, 16, v17
	v_and_b32_e32 v17, 0xffff0000, v17
	v_pk_fma_f32 v[12:13], v[20:21], v[22:23], v[12:13]
	v_lshlrev_b32_e32 v22, 16, v18
	v_pk_fma_f32 v[12:13], v[24:25], v[16:17], v[12:13] op_sel_hi:[0,1,1]
	v_lshlrev_b32_e32 v16, 16, v4
	v_and_b32_e32 v17, 0xffff0000, v14
	v_cvt_pk_bf16_f32 v3, v12, v13
	v_lshlrev_b32_e32 v12, 16, v14
	v_and_b32_e32 v13, 0xffff0000, v4
	v_pk_mul_f32 v[16:17], v[20:21], v[16:17] op_sel:[1,0] op_sel_hi:[0,1]
	v_and_b32_e32 v23, 0xffff0000, v18
	v_pk_fma_f32 v[12:13], v[20:21], v[12:13], v[16:17]
	v_lshlrev_b32_e32 v14, 16, v5
	v_pk_fma_f32 v[12:13], v[24:25], v[22:23], v[12:13] op_sel_hi:[0,1,1]
	v_cvt_pk_bf16_f32 v4, v12, v13
	v_lshlrev_b32_e32 v12, 16, v15
	v_and_b32_e32 v15, 0xffff0000, v15
	v_and_b32_e32 v13, 0xffff0000, v5
	v_pk_mul_f32 v[14:15], v[20:21], v[14:15] op_sel:[1,0] op_sel_hi:[0,1]
	v_pk_fma_f32 v[12:13], v[20:21], v[12:13], v[14:15]
	v_lshlrev_b32_e32 v14, 16, v19
	v_and_b32_e32 v15, 0xffff0000, v19
	v_pk_fma_f32 v[12:13], v[24:25], v[14:15], v[12:13] op_sel_hi:[0,1,1]
	v_cvt_pk_bf16_f32 v5, v12, v13
	v_mov_b64_e32 v[12:13], s[22:23]
	v_mad_i64_i32 v[12:13], s[14:15], v11, s77, v[12:13]
	v_lshlrev_b32_e32 v14, 7, v25
	v_mov_b32_e32 v15, v1
	v_lshl_add_u64 v[12:13], v[12:13], 0, v[14:15]
	v_lshl_add_u64 v[12:13], v[12:13], 0, v[0:1]
	v_add_co_u32_e32 v12, vcc, 0x9c01000, v12
	s_mov_b64 s[14:15], 0xfffff
	s_nop 0
	v_addc_co_u32_e32 v13, vcc, 0, v13, vcc
	v_cmp_lt_i64_e32 vcc, s[14:15], v[6:7]
	v_lshl_add_u64 v[10:11], v[10:11], 0, s[10:11]
	s_or_b64 s[36:37], vcc, s[36:37]
	global_store_dwordx4 v[12:13], v[2:5], off offset:832
	s_andn2_b64 exec, exec, s[36:37]
	s_cbranch_execnz .LBB0_215

; DI float fexp2(float x) { return __builtin_amdgcn_exp2f(x); }
; DI float max3f(float a, float b, float c) { float r; asm("v_max3_f32 %0, %1, %2, %3" : "=v"(r) : "v"(a), "v"(b), "v"(c)); return r; }
; DI float max2f(float a, float b) { float r; asm("v_max_f32_e32 %0, %1, %2" : "=v"(r) : "v"(a), "v"(b)); return r; }
;     ...
;             float mxa = max3f(s0[0], s1[0], s0[1]), mxb = max3f(s1[1], s0[2], s1[2]);
; #pragma unroll
;             for (int i = 3; i < 15; i += 2) { mxa = max3f(mxa, s0[i], s1[i]); mxb = max3f(mxb, s0[i + 1], s1[i + 1]); }
;             float mx = max3f(mxa, mxb, max2f(s0[15], s1[15]));
;             mx = max2f(mx, __shfl_xor(mx, 32));
;             if (__builtin_amdgcn_ballot_w64(mx - m > 8.0f) != 0ull) {
;                 const float mn = fmaxf(m, mx), mu_ = (mn == -INFINITY) ? 0.f : mn;
;                 const float alpha = fexp2(m - mu_); m = mn; l *= alpha;
; #pragma unroll
;                 for (int i = 0; i < 16; ++i) { o0[i] *= alpha; o1[i] *= alpha; }
;             }
.LBB0_251:
	v_max3_f32 v146, v50, v34, v51
	v_max3_f32 v147, v35, v52, v36
	v_max_f32_e32 v148, v65, v49
	s_mov_b32 s1, 0x41000000
	v_max3_f32 v146, v146, v53, v37
	v_max3_f32 v147, v147, v54, v38
	s_nop 0
	v_max3_f32 v146, v146, v55, v39
	v_max3_f32 v147, v147, v56, v40
	s_nop 0
	v_max3_f32 v146, v146, v57, v41
	v_max3_f32 v147, v147, v58, v42
	s_nop 0
	v_max3_f32 v146, v146, v59, v43
	v_max3_f32 v147, v147, v60, v44
	s_nop 0
	v_max3_f32 v146, v146, v61, v45
	v_max3_f32 v147, v147, v62, v46
	s_nop 0
	v_max3_f32 v146, v146, v63, v47
	v_max3_f32 v147, v147, v64, v48
	s_nop 0
	v_max3_f32 v146, v146, v147, v148
	v_mov_b32_e32 v147, v146
	s_nop 1
	v_permlane32_swap_b32_e32 v147, v146
	v_max_f32_e32 v146, v146, v147
	s_nop 0
	v_sub_f32_e32 v147, v146, v145
	v_cmp_lt_f32_e32 vcc, s1, v147
	s_cbranch_vccz .LBB0_253
	v_max_f32_e32 v146, v146, v146
	v_max_f32_e32 v147, v145, v145
	v_max_f32_e32 v147, v147, v146
	v_cmp_neq_f32_e32 vcc, s79, v147
	s_nop 1
	v_cndmask_b32_e32 v146, 0, v147, vcc
	v_sub_f32_e32 v145, v145, v146
	v_exp_f32_e32 v146, v145
	v_mov_b32_e32 v145, v147
	v_mul_f32_e32 v144, v144, v146
	v_mul_f32_e32 v32, v32, v146
	v_mul_f32_e32 v33, v33, v146
	v_mul_f32_e32 v30, v30, v146
	v_mul_f32_e32 v31, v31, v146
	v_mul_f32_e32 v28, v28, v146
	v_mul_f32_e32 v29, v29, v146
	v_mul_f32_e32 v26, v26, v146
	v_mul_f32_e32 v27, v27, v146
	v_mul_f32_e32 v24, v24, v146
	v_mul_f32_e32 v25, v25, v146
	v_mul_f32_e32 v22, v22, v146
	v_mul_f32_e32 v23, v23, v146
	v_mul_f32_e32 v20, v20, v146
	v_mul_f32_e32 v21, v21, v146
	v_mul_f32_e32 v18, v18, v146
	v_mul_f32_e32 v19, v19, v146
	v_mul_f32_e32 v16, v16, v146
	v_mul_f32_e32 v17, v17, v146
	v_mul_f32_e32 v14, v14, v146
	v_mul_f32_e32 v15, v15, v146
	v_mul_f32_e32 v12, v12, v146
	v_mul_f32_e32 v13, v13, v146
	v_mul_f32_e32 v10, v10, v146
	v_mul_f32_e32 v11, v11, v146
	v_mul_f32_e32 v8, v8, v146
	v_mul_f32_e32 v9, v9, v146
	v_mul_f32_e32 v6, v6, v146
	v_mul_f32_e32 v7, v7, v146
	v_mul_f32_e32 v4, v4, v146
	v_mul_f32_e32 v5, v5, v146
	v_mul_f32_e32 v2, v2, v146
	v_mul_f32_e32 v3, v3, v146

; DI unsigned cvtpk(float lo, float hi) { f32x2_t v = {lo, hi}; bf16x2_t b = __builtin_convertvector(v, bf16x2_t); return __builtin_bit_cast(unsigned, b); }
; DI void store_o64(bf16_t* dst, const f32x16& o0, const f32x16& o1, float sc, int h) {
; #pragma unroll
;     for (int q = 0; q < 4; ++q) {
;         u32x2 w; w.x = cvtpk(o0[4 * q] * sc, o0[4 * q + 1] * sc); w.y = cvtpk(o0[4 * q + 2] * sc, o0[4 * q + 3] * sc);
;         *(u32x2*)(dst + 8 * q + 4 * h) = w;
;         u32x2 w2; w2.x = cvtpk(o1[4 * q] * sc, o1[4 * q + 1] * sc); w2.y = cvtpk(o1[4 * q + 2] * sc, o1[4 * q + 3] * sc);
;         *(u32x2*)(dst + 32 + 8 * q + 4 * h) = w2;
;     }
; DI void phase_att0(const Ctx& C, const KA& a) {
;     ...
;             l += __shfl_xor(l, 32);
;             store_o64(z + (size_t)(b * SEQ + t) * LD0 + Z0_MIX + head * 64, o0, o1, 1.0f / l, h);
.LBB0_270:
	v_and_b32_e32 v34, 64, v245
	v_xor_b32_e32 v0, 32, v245
	v_add_u32_e32 v34, 64, v34
	v_cmp_lt_i32_e32 vcc, v0, v34
	s_lshl_b32 s4, s31, 8
	s_and_b32 s4, s4, 0x7800
	v_cndmask_b32_e32 v0, v245, v0, vcc
	v_lshlrev_b32_e32 v0, 2, v0
	ds_bpermute_b32 v0, v0, v144
	v_add_u32_e32 v36, s4, v124
	v_mov_b64_e32 v[34:35], s[74:75]
	v_mad_i64_i32 v[34:35], s[4:5], v36, s77, v[34:35]
	s_waitcnt lgkmcnt(0)
	v_add_f32_e32 v0, v144, v0
	v_div_scale_f32 v36, s[4:5], v0, v0, 1.0
	v_rcp_f32_e32 v37, v36
	s_lshl_b32 s4, s30, 7
	s_and_b32 s46, s4, 0x380
	v_lshl_add_u64 v[34:35], v[34:35], 0, s[46:47]
	v_fma_f32 v38, -v36, v37, 1.0
	v_fmac_f32_e32 v37, v38, v37
	v_div_scale_f32 v38, vcc, 1.0, v0, 1.0
	v_mul_f32_e32 v39, v38, v37
	v_fma_f32 v40, -v36, v39, v38
	v_fmac_f32_e32 v39, v40, v37
	v_fma_f32 v36, -v36, v39, v38
	v_div_fmas_f32 v36, v36, v37, v39
	v_div_fixup_f32 v36, v36, v0, 1.0
	v_lshlrev_b32_e32 v0, 1, v120
	v_mul_f32_e32 v2, v2, v36
	v_mul_f32_e32 v3, v3, v36
	v_mul_f32_e32 v4, v4, v36
	v_mul_f32_e32 v5, v5, v36
	v_lshl_add_u64 v[34:35], v[34:35], 0, v[0:1]
	v_cvt_pk_bf16_f32 v2, v2, v3
	v_cvt_pk_bf16_f32 v3, v4, v5
	global_store_dwordx2 v[34:35], v[2:3], off offset:3968
	v_pk_mul_f32 v[2:3], v[22:23], v[36:37] op_sel_hi:[1,0]
	v_pk_mul_f32 v[4:5], v[24:25], v[36:37] op_sel_hi:[1,0]
	v_cvt_pk_bf16_f32 v2, v2, v3
	v_cvt_pk_bf16_f32 v3, v4, v5
	global_store_dwordx2 v[34:35], v[2:3], off offset:3920
	v_pk_mul_f32 v[2:3], v[6:7], v[36:37] op_sel_hi:[1,0]
	v_pk_mul_f32 v[4:5], v[8:9], v[36:37] op_sel_hi:[1,0]
	v_cvt_pk_bf16_f32 v2, v2, v3
	v_cvt_pk_bf16_f32 v3, v4, v5
	global_store_dwordx2 v[34:35], v[2:3], off offset:3984
	v_pk_mul_f32 v[2:3], v[26:27], v[36:37] op_sel_hi:[1,0]
	v_pk_mul_f32 v[4:5], v[28:29], v[36:37] op_sel_hi:[1,0]
	v_cvt_pk_bf16_f32 v2, v2, v3
	v_cvt_pk_bf16_f32 v3, v4, v5
	global_store_dwordx2 v[34:35], v[2:3], off offset:3936
	v_pk_mul_f32 v[2:3], v[10:11], v[36:37] op_sel_hi:[1,0]
	v_pk_mul_f32 v[4:5], v[12:13], v[36:37] op_sel_hi:[1,0]
	v_cvt_pk_bf16_f32 v2, v2, v3
	v_cvt_pk_bf16_f32 v3, v4, v5
	global_store_dwordx2 v[34:35], v[2:3], off offset:4000
	v_pk_mul_f32 v[2:3], v[30:31], v[36:37] op_sel_hi:[1,0]
	v_pk_mul_f32 v[4:5], v[32:33], v[36:37] op_sel_hi:[1,0]
	v_cvt_pk_bf16_f32 v2, v2, v3
	v_cvt_pk_bf16_f32 v3, v4, v5
	v_mul_f32_e32 v18, v18, v36
	v_mul_f32_e32 v19, v19, v36
	v_mul_f32_e32 v20, v20, v36
	v_mul_f32_e32 v21, v21, v36
	global_store_dwordx2 v[34:35], v[2:3], off offset:3952
	v_pk_mul_f32 v[2:3], v[14:15], v[36:37] op_sel_hi:[1,0]
	v_pk_mul_f32 v[4:5], v[16:17], v[36:37] op_sel_hi:[1,0]
	v_cvt_pk_bf16_f32 v18, v18, v19
	v_cvt_pk_bf16_f32 v19, v20, v21
	v_cvt_pk_bf16_f32 v2, v2, v3
	v_cvt_pk_bf16_f32 v3, v4, v5
	s_mov_b32 s42, 0x35000
	global_store_dwordx2 v[34:35], v[18:19], off offset:3904
	global_store_dwordx2 v[34:35], v[2:3], off offset:4016
	s_mov_b32 s10, 0

; DI float fexp2(float x) { return __builtin_amdgcn_exp2f(x); }
; DI float max3f(float a, float b, float c) { float r; asm("v_max3_f32 %0, %1, %2, %3" : "=v"(r) : "v"(a), "v"(b), "v"(c)); return r; }
; DI float max2f(float a, float b) { float r; asm("v_max_f32_e32 %0, %1, %2" : "=v"(r) : "v"(a), "v"(b)); return r; }
;     ...
;             float mxa = max3f(s0[0], s1[0], s0[1]), mxb = max3f(s1[1], s0[2], s1[2]);
; #pragma unroll
;             for (int i = 3; i < 15; i += 2) { mxa = max3f(mxa, s0[i], s1[i]); mxb = max3f(mxb, s0[i + 1], s1[i + 1]); }
;             float mx = max3f(mxa, mxb, max2f(s0[15], s1[15]));
;             mx = max2f(mx, __shfl_xor(mx, 32));
;             if (__builtin_amdgcn_ballot_w64(mx - m > 8.0f) != 0ull) {
;                 const float mn = fmaxf(m, mx), mu_ = (mn == -INFINITY) ? 0.f : mn;
;                 const float alpha = fexp2(m - mu_); m = mn; l *= alpha;
; #pragma unroll
;                 for (int i = 0; i < 16; ++i) { o0[i] *= alpha; o1[i] *= alpha; }
;             }
.LBB0_317:
	v_max3_f32 v123, v50, v34, v51
	v_max3_f32 v124, v35, v52, v36
	v_max_f32_e32 v125, v65, v49
	s_mov_b32 s1, 0x41000000
	v_max3_f32 v123, v123, v53, v37
	v_max3_f32 v124, v124, v54, v38
	s_mov_b32 s42, 0x35000
	v_max3_f32 v123, v123, v55, v39
	v_max3_f32 v124, v124, v56, v40
	s_nop 0
	v_max3_f32 v123, v123, v57, v41
	v_max3_f32 v124, v124, v58, v42
	s_nop 0
	v_max3_f32 v123, v123, v59, v43
	v_max3_f32 v124, v124, v60, v44
	s_nop 0
	v_max3_f32 v123, v123, v61, v45
	v_max3_f32 v124, v124, v62, v46
	s_nop 0
	v_max3_f32 v123, v123, v63, v47
	v_max3_f32 v124, v124, v64, v48
	s_nop 0
	v_max3_f32 v123, v123, v124, v125
	v_mov_b32_e32 v124, v123
	s_nop 1
	v_permlane32_swap_b32_e32 v124, v123
	v_max_f32_e32 v123, v123, v124
	s_nop 0
	v_sub_f32_e32 v124, v123, v112
	v_cmp_lt_f32_e32 vcc, s1, v124
	s_cbranch_vccz .LBB0_319
	v_max_f32_e32 v123, v123, v123
	v_max_f32_e32 v124, v112, v112
	v_max_f32_e32 v123, v124, v123
	v_cmp_neq_f32_e32 vcc, s79, v123
	s_nop 1
	v_cndmask_b32_e32 v124, 0, v123, vcc
	v_sub_f32_e32 v112, v112, v124
	v_exp_f32_e32 v112, v112
	s_nop 0
	v_mul_f32_e32 v105, v105, v112
	v_mul_f32_e32 v32, v32, v112
	v_mul_f32_e32 v33, v33, v112
	v_mul_f32_e32 v30, v30, v112
	v_mul_f32_e32 v31, v31, v112
	v_mul_f32_e32 v28, v28, v112
	v_mul_f32_e32 v29, v29, v112
	v_mul_f32_e32 v26, v26, v112
	v_mul_f32_e32 v27, v27, v112
	v_mul_f32_e32 v24, v24, v112
	v_mul_f32_e32 v25, v25, v112
	v_mul_f32_e32 v22, v22, v112
	v_mul_f32_e32 v23, v23, v112
	v_mul_f32_e32 v20, v20, v112
	v_mul_f32_e32 v21, v21, v112
	v_mul_f32_e32 v18, v18, v112
	v_mul_f32_e32 v19, v19, v112
	v_mul_f32_e32 v16, v16, v112
	v_mul_f32_e32 v17, v17, v112
	v_mul_f32_e32 v14, v14, v112
	v_mul_f32_e32 v15, v15, v112
	v_mul_f32_e32 v12, v12, v112
	v_mul_f32_e32 v13, v13, v112
	v_mul_f32_e32 v10, v10, v112
	v_mul_f32_e32 v11, v11, v112
	v_mul_f32_e32 v8, v8, v112
	v_mul_f32_e32 v9, v9, v112
	v_mul_f32_e32 v6, v6, v112
	v_mul_f32_e32 v7, v7, v112
	v_mul_f32_e32 v4, v4, v112
	v_mul_f32_e32 v5, v5, v112
	v_mul_f32_e32 v2, v2, v112
	v_mul_f32_e32 v3, v3, v112
	v_mov_b32_e32 v112, v123

; DI float fexp2(float x) { return __builtin_amdgcn_exp2f(x); }
; DI float max3f(float a, float b, float c) { float r; asm("v_max3_f32 %0, %1, %2, %3" : "=v"(r) : "v"(a), "v"(b), "v"(c)); return r; }
; DI float max2f(float a, float b) { float r; asm("v_max_f32_e32 %0, %1, %2" : "=v"(r) : "v"(a), "v"(b)); return r; }
;     ...
;             float mxa = max3f(s0[0], s1[0], s0[1]), mxb = max3f(s1[1], s0[2], s1[2]);
; #pragma unroll
;             for (int i = 3; i < 15; i += 2) { mxa = max3f(mxa, s0[i], s1[i]); mxb = max3f(mxb, s0[i + 1], s1[i + 1]); }
;             float mx = max3f(mxa, mxb, max2f(s0[15], s1[15]));
;             mx = max2f(mx, __shfl_xor(mx, 32));
;             if (__builtin_amdgcn_ballot_w64(mx - m > 8.0f) != 0ull) {
;                 const float mn = fmaxf(m, mx), mu_ = (mn == -INFINITY) ? 0.f : mn;
;                 const float alpha = fexp2(m - mu_); m = mn; l *= alpha;
; #pragma unroll
;                 for (int i = 0; i < 16; ++i) { o0[i] *= alpha; o1[i] *= alpha; }
;             }
.LBB0_331:
	v_max3_f32 v123, v34, v50, v35
	v_max3_f32 v124, v51, v36, v52
	v_max_f32_e32 v125, v49, v65
	s_mov_b32 s0, 0x41000000
	v_max3_f32 v123, v123, v37, v53
	v_max3_f32 v124, v124, v38, v54
	s_nop 0
	v_max3_f32 v123, v123, v39, v55
	v_max3_f32 v124, v124, v40, v56
	s_nop 0
	v_max3_f32 v123, v123, v41, v57
	v_max3_f32 v124, v124, v42, v58
	s_nop 0
	v_max3_f32 v123, v123, v43, v59
	v_max3_f32 v124, v124, v44, v60
	s_nop 0
	v_max3_f32 v123, v123, v45, v61
	v_max3_f32 v124, v124, v46, v62
	s_nop 0
	v_max3_f32 v123, v123, v47, v63
	v_max3_f32 v124, v124, v48, v64
	s_nop 0
	v_max3_f32 v123, v123, v124, v125
	v_mov_b32_e32 v124, v123
	s_nop 1
	v_permlane32_swap_b32_e32 v124, v123
	v_max_f32_e32 v123, v123, v124
	s_nop 0
	v_sub_f32_e32 v124, v123, v112
	v_cmp_lt_f32_e32 vcc, s0, v124
	s_cbranch_vccz .LBB0_333
	v_max_f32_e32 v123, v123, v123
	v_max_f32_e32 v124, v112, v112
	v_max_f32_e32 v123, v124, v123
	v_cmp_neq_f32_e32 vcc, s79, v123
	s_nop 1
	v_cndmask_b32_e32 v124, 0, v123, vcc
	v_sub_f32_e32 v112, v112, v124
	v_exp_f32_e32 v112, v112
	s_nop 0
	v_mul_f32_e32 v105, v105, v112
	v_mul_f32_e32 v32, v32, v112
	v_mul_f32_e32 v33, v33, v112
	v_mul_f32_e32 v30, v30, v112
	v_mul_f32_e32 v31, v31, v112
	v_mul_f32_e32 v28, v28, v112
	v_mul_f32_e32 v29, v29, v112
	v_mul_f32_e32 v26, v26, v112
	v_mul_f32_e32 v27, v27, v112
	v_mul_f32_e32 v24, v24, v112
	v_mul_f32_e32 v25, v25, v112
	v_mul_f32_e32 v22, v22, v112
	v_mul_f32_e32 v23, v23, v112
	v_mul_f32_e32 v20, v20, v112
	v_mul_f32_e32 v21, v21, v112
	v_mul_f32_e32 v18, v18, v112
	v_mul_f32_e32 v19, v19, v112
	v_mul_f32_e32 v16, v16, v112
	v_mul_f32_e32 v17, v17, v112
	v_mul_f32_e32 v14, v14, v112
	v_mul_f32_e32 v15, v15, v112
	v_mul_f32_e32 v12, v12, v112
	v_mul_f32_e32 v13, v13, v112
	v_mul_f32_e32 v10, v10, v112
	v_mul_f32_e32 v11, v11, v112
	v_mul_f32_e32 v8, v8, v112
	v_mul_f32_e32 v9, v9, v112
	v_mul_f32_e32 v6, v6, v112
	v_mul_f32_e32 v7, v7, v112
	v_mul_f32_e32 v4, v4, v112
	v_mul_f32_e32 v5, v5, v112
	v_mul_f32_e32 v2, v2, v112
	v_mul_f32_e32 v3, v3, v112
	v_mov_b32_e32 v112, v123
